# FFN up-projection SwiGLU epilogue rewritten: packed f32 scale and +1, 32-bit saddr stores (same operations and order per element)
# speedup vs baseline: 1.0038x; 1.0010x over previous
.LBB0_70:
	v_lshl_or_b32 v144, s50, 7, v142
	v_lshl_add_u32 v145, s26, 8, v140
	v_lshlrev_b32_e32 v144, 1, v144
	v_mov_b32_e32 v138, 0xbfb8aa3b
	v_mov_b32_e32 v139, 0xbfb8aa3b
	v_mad_u32_u24 v154, v145, s33, v144
	v_mov_b32_e32 v152, 1.0
	v_mov_b32_e32 v153, 1.0
	v_pk_mul_f32 v[144:145], v[124:125], v[138:139]
	v_pk_mul_f32 v[146:147], v[126:127], v[138:139]
	v_pk_mul_f32 v[148:149], v[120:121], v[138:139]
	v_pk_mul_f32 v[150:151], v[122:123], v[138:139]
	v_exp_f32_e32 v144, v144
	v_exp_f32_e32 v145, v145
	v_exp_f32_e32 v146, v146
	v_exp_f32_e32 v147, v147
	v_exp_f32_e32 v148, v148
	v_exp_f32_e32 v149, v149
	v_exp_f32_e32 v150, v150
	v_exp_f32_e32 v151, v151
	v_pk_add_f32 v[144:145], v[144:145], v[152:153]
	v_pk_add_f32 v[146:147], v[146:147], v[152:153]
	v_pk_add_f32 v[148:149], v[148:149], v[152:153]
	v_pk_add_f32 v[150:151], v[150:151], v[152:153]
	v_rcp_f32_e32 v144, v144
	v_rcp_f32_e32 v145, v145
	v_rcp_f32_e32 v146, v146
	v_rcp_f32_e32 v147, v147
	v_rcp_f32_e32 v148, v148
	v_rcp_f32_e32 v149, v149
	v_rcp_f32_e32 v150, v150
	v_rcp_f32_e32 v151, v151
	v_pk_mul_f32 v[124:125], v[124:125], v[144:145]
	v_pk_mul_f32 v[126:127], v[126:127], v[146:147]
	v_pk_mul_f32 v[120:121], v[120:121], v[148:149]
	v_pk_mul_f32 v[122:123], v[122:123], v[150:151]
	v_pk_mul_f32 v[124:125], v[124:125], v[116:117]
	v_pk_mul_f32 v[126:127], v[126:127], v[118:119]
	v_pk_mul_f32 v[120:121], v[120:121], v[112:113]
	v_pk_mul_f32 v[122:123], v[122:123], v[114:115]
	v_cvt_pk_bf16_f32 v124, v124, v125
	v_cvt_pk_bf16_f32 v125, v126, v127
	v_cvt_pk_bf16_f32 v126, v120, v121
	v_cvt_pk_bf16_f32 v127, v122, v123
	global_store_dwordx4 v154, v[124:127], s[12:13]
	v_pk_mul_f32 v[144:145], v[108:109], v[138:139]
	v_pk_mul_f32 v[146:147], v[110:111], v[138:139]
	v_pk_mul_f32 v[148:149], v[104:105], v[138:139]
	v_pk_mul_f32 v[150:151], v[106:107], v[138:139]
	v_exp_f32_e32 v144, v144
	v_exp_f32_e32 v145, v145
	v_exp_f32_e32 v146, v146
	v_exp_f32_e32 v147, v147
	v_exp_f32_e32 v148, v148
	v_exp_f32_e32 v149, v149
	v_exp_f32_e32 v150, v150
	v_exp_f32_e32 v151, v151
	v_pk_add_f32 v[144:145], v[144:145], v[152:153]
	v_pk_add_f32 v[146:147], v[146:147], v[152:153]
	v_pk_add_f32 v[148:149], v[148:149], v[152:153]
	v_pk_add_f32 v[150:151], v[150:151], v[152:153]
	v_rcp_f32_e32 v144, v144
	v_rcp_f32_e32 v145, v145
	v_rcp_f32_e32 v146, v146
	v_rcp_f32_e32 v147, v147
	v_rcp_f32_e32 v148, v148
	v_rcp_f32_e32 v149, v149
	v_rcp_f32_e32 v150, v150
	v_rcp_f32_e32 v151, v151
	v_pk_mul_f32 v[108:109], v[108:109], v[144:145]
	v_pk_mul_f32 v[110:111], v[110:111], v[146:147]
	v_pk_mul_f32 v[104:105], v[104:105], v[148:149]
	v_pk_mul_f32 v[106:107], v[106:107], v[150:151]
	v_pk_mul_f32 v[108:109], v[108:109], v[100:101]
	v_pk_mul_f32 v[110:111], v[110:111], v[102:103]
	v_pk_mul_f32 v[104:105], v[104:105], v[96:97]
	v_pk_mul_f32 v[106:107], v[106:107], v[98:99]
	v_cvt_pk_bf16_f32 v108, v108, v109
	v_cvt_pk_bf16_f32 v109, v110, v111
	v_cvt_pk_bf16_f32 v110, v104, v105
	v_cvt_pk_bf16_f32 v111, v106, v107
	v_add_u32_e32 v155, 0x16000, v154
	global_store_dwordx4 v155, v[108:111], s[12:13]
	v_pk_mul_f32 v[144:145], v[92:93], v[138:139]
	v_pk_mul_f32 v[146:147], v[94:95], v[138:139]
	v_pk_mul_f32 v[148:149], v[88:89], v[138:139]
	v_pk_mul_f32 v[150:151], v[90:91], v[138:139]
	v_exp_f32_e32 v144, v144
	v_exp_f32_e32 v145, v145
	v_exp_f32_e32 v146, v146
	v_exp_f32_e32 v147, v147
	v_exp_f32_e32 v148, v148
	v_exp_f32_e32 v149, v149
	v_exp_f32_e32 v150, v150
	v_exp_f32_e32 v151, v151
	v_pk_add_f32 v[144:145], v[144:145], v[152:153]
	v_pk_add_f32 v[146:147], v[146:147], v[152:153]
	v_pk_add_f32 v[148:149], v[148:149], v[152:153]
	v_pk_add_f32 v[150:151], v[150:151], v[152:153]
	v_rcp_f32_e32 v144, v144
	v_rcp_f32_e32 v145, v145
	v_rcp_f32_e32 v146, v146
	v_rcp_f32_e32 v147, v147
	v_rcp_f32_e32 v148, v148
	v_rcp_f32_e32 v149, v149
	v_rcp_f32_e32 v150, v150
	v_rcp_f32_e32 v151, v151
	v_pk_mul_f32 v[92:93], v[92:93], v[144:145]
	v_pk_mul_f32 v[94:95], v[94:95], v[146:147]
	v_pk_mul_f32 v[88:89], v[88:89], v[148:149]
	v_pk_mul_f32 v[90:91], v[90:91], v[150:151]
	v_pk_mul_f32 v[92:93], v[92:93], v[84:85]
	v_pk_mul_f32 v[94:95], v[94:95], v[86:87]
	v_pk_mul_f32 v[88:89], v[88:89], v[80:81]
	v_pk_mul_f32 v[90:91], v[90:91], v[82:83]
	v_cvt_pk_bf16_f32 v92, v92, v93
	v_cvt_pk_bf16_f32 v93, v94, v95
	v_cvt_pk_bf16_f32 v94, v88, v89
	v_cvt_pk_bf16_f32 v95, v90, v91
	v_add_u32_e32 v155, 0x2c000, v154
	global_store_dwordx4 v155, v[92:95], s[12:13]
	v_pk_mul_f32 v[144:145], v[76:77], v[138:139]
	v_pk_mul_f32 v[146:147], v[78:79], v[138:139]
	v_pk_mul_f32 v[148:149], v[72:73], v[138:139]
	v_pk_mul_f32 v[150:151], v[74:75], v[138:139]
	v_exp_f32_e32 v144, v144
	v_exp_f32_e32 v145, v145
	v_exp_f32_e32 v146, v146
	v_exp_f32_e32 v147, v147
	v_exp_f32_e32 v148, v148
	v_exp_f32_e32 v149, v149
	v_exp_f32_e32 v150, v150
	v_exp_f32_e32 v151, v151
	v_pk_add_f32 v[144:145], v[144:145], v[152:153]
	v_pk_add_f32 v[146:147], v[146:147], v[152:153]
	v_pk_add_f32 v[148:149], v[148:149], v[152:153]
	v_pk_add_f32 v[150:151], v[150:151], v[152:153]
	v_rcp_f32_e32 v144, v144
	v_rcp_f32_e32 v145, v145
	v_rcp_f32_e32 v146, v146
	v_rcp_f32_e32 v147, v147
	v_rcp_f32_e32 v148, v148
	v_rcp_f32_e32 v149, v149
	v_rcp_f32_e32 v150, v150
	v_rcp_f32_e32 v151, v151
	v_pk_mul_f32 v[76:77], v[76:77], v[144:145]
	v_pk_mul_f32 v[78:79], v[78:79], v[146:147]
	v_pk_mul_f32 v[72:73], v[72:73], v[148:149]
	v_pk_mul_f32 v[74:75], v[74:75], v[150:151]
	v_pk_mul_f32 v[76:77], v[76:77], v[68:69]
	v_pk_mul_f32 v[78:79], v[78:79], v[70:71]
	v_pk_mul_f32 v[72:73], v[72:73], v[64:65]
	v_pk_mul_f32 v[74:75], v[74:75], v[66:67]
	v_cvt_pk_bf16_f32 v76, v76, v77
	v_cvt_pk_bf16_f32 v77, v78, v79
	v_cvt_pk_bf16_f32 v78, v72, v73
	v_cvt_pk_bf16_f32 v79, v74, v75
	v_add_u32_e32 v155, 0x42000, v154
	global_store_dwordx4 v155, v[76:79], s[12:13]
	v_pk_mul_f32 v[144:145], v[60:61], v[138:139]
	v_pk_mul_f32 v[146:147], v[62:63], v[138:139]
	v_pk_mul_f32 v[148:149], v[56:57], v[138:139]
	v_pk_mul_f32 v[150:151], v[58:59], v[138:139]
	v_exp_f32_e32 v144, v144
	v_exp_f32_e32 v145, v145
	v_exp_f32_e32 v146, v146
	v_exp_f32_e32 v147, v147
	v_exp_f32_e32 v148, v148
	v_exp_f32_e32 v149, v149
	v_exp_f32_e32 v150, v150
	v_exp_f32_e32 v151, v151
	v_pk_add_f32 v[144:145], v[144:145], v[152:153]
	v_pk_add_f32 v[146:147], v[146:147], v[152:153]
	v_pk_add_f32 v[148:149], v[148:149], v[152:153]
	v_pk_add_f32 v[150:151], v[150:151], v[152:153]
	v_rcp_f32_e32 v144, v144
	v_rcp_f32_e32 v145, v145
	v_rcp_f32_e32 v146, v146
	v_rcp_f32_e32 v147, v147
	v_rcp_f32_e32 v148, v148
	v_rcp_f32_e32 v149, v149
	v_rcp_f32_e32 v150, v150
	v_rcp_f32_e32 v151, v151
	v_pk_mul_f32 v[60:61], v[60:61], v[144:145]
	v_pk_mul_f32 v[62:63], v[62:63], v[146:147]
	v_pk_mul_f32 v[56:57], v[56:57], v[148:149]
	v_pk_mul_f32 v[58:59], v[58:59], v[150:151]
	v_pk_mul_f32 v[60:61], v[60:61], v[52:53]
	v_pk_mul_f32 v[62:63], v[62:63], v[54:55]
	v_pk_mul_f32 v[56:57], v[56:57], v[48:49]
	v_pk_mul_f32 v[58:59], v[58:59], v[50:51]
	v_cvt_pk_bf16_f32 v60, v60, v61
	v_cvt_pk_bf16_f32 v61, v62, v63
	v_cvt_pk_bf16_f32 v62, v56, v57
	v_cvt_pk_bf16_f32 v63, v58, v59
	v_add_u32_e32 v155, 0xb0000, v154
	global_store_dwordx4 v155, v[60:63], s[12:13]
	v_pk_mul_f32 v[144:145], v[44:45], v[138:139]
	v_pk_mul_f32 v[146:147], v[46:47], v[138:139]
	v_pk_mul_f32 v[148:149], v[40:41], v[138:139]
	v_pk_mul_f32 v[150:151], v[42:43], v[138:139]
	v_exp_f32_e32 v144, v144
	v_exp_f32_e32 v145, v145
	v_exp_f32_e32 v146, v146
	v_exp_f32_e32 v147, v147
	v_exp_f32_e32 v148, v148
	v_exp_f32_e32 v149, v149
	v_exp_f32_e32 v150, v150
	v_exp_f32_e32 v151, v151
	v_pk_add_f32 v[144:145], v[144:145], v[152:153]
	v_pk_add_f32 v[146:147], v[146:147], v[152:153]
	v_pk_add_f32 v[148:149], v[148:149], v[152:153]
	v_pk_add_f32 v[150:151], v[150:151], v[152:153]
	v_rcp_f32_e32 v144, v144
	v_rcp_f32_e32 v145, v145
	v_rcp_f32_e32 v146, v146
	v_rcp_f32_e32 v147, v147
	v_rcp_f32_e32 v148, v148
	v_rcp_f32_e32 v149, v149
	v_rcp_f32_e32 v150, v150
	v_rcp_f32_e32 v151, v151
	v_pk_mul_f32 v[44:45], v[44:45], v[144:145]
	v_pk_mul_f32 v[46:47], v[46:47], v[146:147]
	v_pk_mul_f32 v[40:41], v[40:41], v[148:149]
	v_pk_mul_f32 v[42:43], v[42:43], v[150:151]
	v_pk_mul_f32 v[44:45], v[44:45], v[36:37]
	v_pk_mul_f32 v[46:47], v[46:47], v[38:39]
	v_pk_mul_f32 v[40:41], v[40:41], v[32:33]
	v_pk_mul_f32 v[42:43], v[42:43], v[34:35]
	v_cvt_pk_bf16_f32 v44, v44, v45
	v_cvt_pk_bf16_f32 v45, v46, v47
	v_cvt_pk_bf16_f32 v46, v40, v41
	v_cvt_pk_bf16_f32 v47, v42, v43
	v_add_u32_e32 v155, 0xc6000, v154
	global_store_dwordx4 v155, v[44:47], s[12:13]
	v_pk_mul_f32 v[144:145], v[28:29], v[138:139]
	v_pk_mul_f32 v[146:147], v[30:31], v[138:139]
	v_pk_mul_f32 v[148:149], v[24:25], v[138:139]
	v_pk_mul_f32 v[150:151], v[26:27], v[138:139]
	v_exp_f32_e32 v144, v144
	v_exp_f32_e32 v145, v145
	v_exp_f32_e32 v146, v146
	v_exp_f32_e32 v147, v147
	v_exp_f32_e32 v148, v148
	v_exp_f32_e32 v149, v149
	v_exp_f32_e32 v150, v150
	v_exp_f32_e32 v151, v151
	v_pk_add_f32 v[144:145], v[144:145], v[152:153]
	v_pk_add_f32 v[146:147], v[146:147], v[152:153]
	v_pk_add_f32 v[148:149], v[148:149], v[152:153]
	v_pk_add_f32 v[150:151], v[150:151], v[152:153]
	v_rcp_f32_e32 v144, v144
	v_rcp_f32_e32 v145, v145
	v_rcp_f32_e32 v146, v146
	v_rcp_f32_e32 v147, v147
	v_rcp_f32_e32 v148, v148
	v_rcp_f32_e32 v149, v149
	v_rcp_f32_e32 v150, v150
	v_rcp_f32_e32 v151, v151
	v_pk_mul_f32 v[28:29], v[28:29], v[144:145]
	v_pk_mul_f32 v[30:31], v[30:31], v[146:147]
	v_pk_mul_f32 v[24:25], v[24:25], v[148:149]
	v_pk_mul_f32 v[26:27], v[26:27], v[150:151]
	v_pk_mul_f32 v[28:29], v[28:29], v[20:21]
	v_pk_mul_f32 v[30:31], v[30:31], v[22:23]
	v_pk_mul_f32 v[24:25], v[24:25], v[16:17]
	v_pk_mul_f32 v[26:27], v[26:27], v[18:19]
	v_cvt_pk_bf16_f32 v28, v28, v29
	v_cvt_pk_bf16_f32 v29, v30, v31
	v_cvt_pk_bf16_f32 v30, v24, v25
	v_cvt_pk_bf16_f32 v31, v26, v27
	v_add_u32_e32 v155, 0xdc000, v154
	global_store_dwordx4 v155, v[28:31], s[12:13]
	v_pk_mul_f32 v[144:145], v[12:13], v[138:139]
	v_pk_mul_f32 v[146:147], v[14:15], v[138:139]
	v_pk_mul_f32 v[148:149], v[8:9], v[138:139]
	v_pk_mul_f32 v[150:151], v[10:11], v[138:139]
	v_exp_f32_e32 v144, v144
	v_exp_f32_e32 v145, v145
	v_exp_f32_e32 v146, v146
	v_exp_f32_e32 v147, v147
	v_exp_f32_e32 v148, v148
	v_exp_f32_e32 v149, v149
	v_exp_f32_e32 v150, v150
	v_exp_f32_e32 v151, v151
	v_pk_add_f32 v[144:145], v[144:145], v[152:153]
	v_pk_add_f32 v[146:147], v[146:147], v[152:153]
	v_pk_add_f32 v[148:149], v[148:149], v[152:153]
	v_pk_add_f32 v[150:151], v[150:151], v[152:153]
	v_rcp_f32_e32 v144, v144
	v_rcp_f32_e32 v145, v145
	v_rcp_f32_e32 v146, v146
	v_rcp_f32_e32 v147, v147
	v_rcp_f32_e32 v148, v148
	v_rcp_f32_e32 v149, v149
	v_rcp_f32_e32 v150, v150
	v_rcp_f32_e32 v151, v151
	v_pk_mul_f32 v[12:13], v[12:13], v[144:145]
	v_pk_mul_f32 v[14:15], v[14:15], v[146:147]
	v_pk_mul_f32 v[8:9], v[8:9], v[148:149]
	v_pk_mul_f32 v[10:11], v[10:11], v[150:151]
	v_pk_mul_f32 v[12:13], v[12:13], v[4:5]
	v_pk_mul_f32 v[14:15], v[14:15], v[6:7]
	v_pk_mul_f32 v[8:9], v[8:9], v[0:1]
	v_pk_mul_f32 v[10:11], v[10:11], v[2:3]
	v_cvt_pk_bf16_f32 v12, v12, v13
	v_cvt_pk_bf16_f32 v13, v14, v15
	v_cvt_pk_bf16_f32 v14, v8, v9
	v_cvt_pk_bf16_f32 v15, v10, v11
	v_add_u32_e32 v155, 0xf2000, v154
	global_store_dwordx4 v155, v[12:15], s[12:13]
	s_mov_b64 s[4:5], -1
	s_andn2_b64 vcc, exec, s[38:39]
	s_cbranch_vccnz .LBB0_63
	s_andn2_b64 vcc, exec, s[10:11]
	s_cbranch_vccnz .LBB0_62
	s_barrier
	s_branch .LBB0_62

.LBB0_940:
	v_lshl_or_b32 v144, s50, 7, v142
	v_lshl_add_u32 v145, s26, 8, v140
	v_lshlrev_b32_e32 v144, 1, v144
	v_mov_b32_e32 v138, 0xbfb8aa3b
	v_mov_b32_e32 v139, 0xbfb8aa3b
	v_mad_u32_u24 v154, v145, s33, v144
	v_mov_b32_e32 v152, 1.0
	v_mov_b32_e32 v153, 1.0
	v_pk_mul_f32 v[144:145], v[124:125], v[138:139]
	v_pk_mul_f32 v[146:147], v[126:127], v[138:139]
	v_pk_mul_f32 v[148:149], v[120:121], v[138:139]
	v_pk_mul_f32 v[150:151], v[122:123], v[138:139]
	v_exp_f32_e32 v144, v144
	v_exp_f32_e32 v145, v145
	v_exp_f32_e32 v146, v146
	v_exp_f32_e32 v147, v147
	v_exp_f32_e32 v148, v148
	v_exp_f32_e32 v149, v149
	v_exp_f32_e32 v150, v150
	v_exp_f32_e32 v151, v151
	v_pk_add_f32 v[144:145], v[144:145], v[152:153]
	v_pk_add_f32 v[146:147], v[146:147], v[152:153]
	v_pk_add_f32 v[148:149], v[148:149], v[152:153]
	v_pk_add_f32 v[150:151], v[150:151], v[152:153]
	v_rcp_f32_e32 v144, v144
	v_rcp_f32_e32 v145, v145
	v_rcp_f32_e32 v146, v146
	v_rcp_f32_e32 v147, v147
	v_rcp_f32_e32 v148, v148
	v_rcp_f32_e32 v149, v149
	v_rcp_f32_e32 v150, v150
	v_rcp_f32_e32 v151, v151
	v_pk_mul_f32 v[124:125], v[124:125], v[144:145]
	v_pk_mul_f32 v[126:127], v[126:127], v[146:147]
	v_pk_mul_f32 v[120:121], v[120:121], v[148:149]
	v_pk_mul_f32 v[122:123], v[122:123], v[150:151]
	v_pk_mul_f32 v[124:125], v[124:125], v[116:117]
	v_pk_mul_f32 v[126:127], v[126:127], v[118:119]
	v_pk_mul_f32 v[120:121], v[120:121], v[112:113]
	v_pk_mul_f32 v[122:123], v[122:123], v[114:115]
	v_cvt_pk_bf16_f32 v124, v124, v125
	v_cvt_pk_bf16_f32 v125, v126, v127
	v_cvt_pk_bf16_f32 v126, v120, v121
	v_cvt_pk_bf16_f32 v127, v122, v123
	global_store_dwordx4 v154, v[124:127], s[10:11]
	v_pk_mul_f32 v[144:145], v[108:109], v[138:139]
	v_pk_mul_f32 v[146:147], v[110:111], v[138:139]
	v_pk_mul_f32 v[148:149], v[104:105], v[138:139]
	v_pk_mul_f32 v[150:151], v[106:107], v[138:139]
	v_exp_f32_e32 v144, v144
	v_exp_f32_e32 v145, v145
	v_exp_f32_e32 v146, v146
	v_exp_f32_e32 v147, v147
	v_exp_f32_e32 v148, v148
	v_exp_f32_e32 v149, v149
	v_exp_f32_e32 v150, v150
	v_exp_f32_e32 v151, v151
	v_pk_add_f32 v[144:145], v[144:145], v[152:153]
	v_pk_add_f32 v[146:147], v[146:147], v[152:153]
	v_pk_add_f32 v[148:149], v[148:149], v[152:153]
	v_pk_add_f32 v[150:151], v[150:151], v[152:153]
	v_rcp_f32_e32 v144, v144
	v_rcp_f32_e32 v145, v145
	v_rcp_f32_e32 v146, v146
	v_rcp_f32_e32 v147, v147
	v_rcp_f32_e32 v148, v148
	v_rcp_f32_e32 v149, v149
	v_rcp_f32_e32 v150, v150
	v_rcp_f32_e32 v151, v151
	v_pk_mul_f32 v[108:109], v[108:109], v[144:145]
	v_pk_mul_f32 v[110:111], v[110:111], v[146:147]
	v_pk_mul_f32 v[104:105], v[104:105], v[148:149]
	v_pk_mul_f32 v[106:107], v[106:107], v[150:151]
	v_pk_mul_f32 v[108:109], v[108:109], v[100:101]
	v_pk_mul_f32 v[110:111], v[110:111], v[102:103]
	v_pk_mul_f32 v[104:105], v[104:105], v[96:97]
	v_pk_mul_f32 v[106:107], v[106:107], v[98:99]
	v_cvt_pk_bf16_f32 v108, v108, v109
	v_cvt_pk_bf16_f32 v109, v110, v111
	v_cvt_pk_bf16_f32 v110, v104, v105
	v_cvt_pk_bf16_f32 v111, v106, v107
	v_add_u32_e32 v155, 0x16000, v154
	global_store_dwordx4 v155, v[108:111], s[10:11]
	v_pk_mul_f32 v[144:145], v[92:93], v[138:139]
	v_pk_mul_f32 v[146:147], v[94:95], v[138:139]
	v_pk_mul_f32 v[148:149], v[88:89], v[138:139]
	v_pk_mul_f32 v[150:151], v[90:91], v[138:139]
	v_exp_f32_e32 v144, v144
	v_exp_f32_e32 v145, v145
	v_exp_f32_e32 v146, v146
	v_exp_f32_e32 v147, v147
	v_exp_f32_e32 v148, v148
	v_exp_f32_e32 v149, v149
	v_exp_f32_e32 v150, v150
	v_exp_f32_e32 v151, v151
	v_pk_add_f32 v[144:145], v[144:145], v[152:153]
	v_pk_add_f32 v[146:147], v[146:147], v[152:153]
	v_pk_add_f32 v[148:149], v[148:149], v[152:153]
	v_pk_add_f32 v[150:151], v[150:151], v[152:153]
	v_rcp_f32_e32 v144, v144
	v_rcp_f32_e32 v145, v145
	v_rcp_f32_e32 v146, v146
	v_rcp_f32_e32 v147, v147
	v_rcp_f32_e32 v148, v148
	v_rcp_f32_e32 v149, v149
	v_rcp_f32_e32 v150, v150
	v_rcp_f32_e32 v151, v151
	v_pk_mul_f32 v[92:93], v[92:93], v[144:145]
	v_pk_mul_f32 v[94:95], v[94:95], v[146:147]
	v_pk_mul_f32 v[88:89], v[88:89], v[148:149]
	v_pk_mul_f32 v[90:91], v[90:91], v[150:151]
	v_pk_mul_f32 v[92:93], v[92:93], v[84:85]
	v_pk_mul_f32 v[94:95], v[94:95], v[86:87]
	v_pk_mul_f32 v[88:89], v[88:89], v[80:81]
	v_pk_mul_f32 v[90:91], v[90:91], v[82:83]
	v_cvt_pk_bf16_f32 v92, v92, v93
	v_cvt_pk_bf16_f32 v93, v94, v95
	v_cvt_pk_bf16_f32 v94, v88, v89
	v_cvt_pk_bf16_f32 v95, v90, v91
	v_add_u32_e32 v155, 0x2c000, v154
	global_store_dwordx4 v155, v[92:95], s[10:11]
	v_pk_mul_f32 v[144:145], v[76:77], v[138:139]
	v_pk_mul_f32 v[146:147], v[78:79], v[138:139]
	v_pk_mul_f32 v[148:149], v[72:73], v[138:139]
	v_pk_mul_f32 v[150:151], v[74:75], v[138:139]
	v_exp_f32_e32 v144, v144
	v_exp_f32_e32 v145, v145
	v_exp_f32_e32 v146, v146
	v_exp_f32_e32 v147, v147
	v_exp_f32_e32 v148, v148
	v_exp_f32_e32 v149, v149
	v_exp_f32_e32 v150, v150
	v_exp_f32_e32 v151, v151
	v_pk_add_f32 v[144:145], v[144:145], v[152:153]
	v_pk_add_f32 v[146:147], v[146:147], v[152:153]
	v_pk_add_f32 v[148:149], v[148:149], v[152:153]
	v_pk_add_f32 v[150:151], v[150:151], v[152:153]
	v_rcp_f32_e32 v144, v144
	v_rcp_f32_e32 v145, v145
	v_rcp_f32_e32 v146, v146
	v_rcp_f32_e32 v147, v147
	v_rcp_f32_e32 v148, v148
	v_rcp_f32_e32 v149, v149
	v_rcp_f32_e32 v150, v150
	v_rcp_f32_e32 v151, v151
	v_pk_mul_f32 v[76:77], v[76:77], v[144:145]
	v_pk_mul_f32 v[78:79], v[78:79], v[146:147]
	v_pk_mul_f32 v[72:73], v[72:73], v[148:149]
	v_pk_mul_f32 v[74:75], v[74:75], v[150:151]
	v_pk_mul_f32 v[76:77], v[76:77], v[68:69]
	v_pk_mul_f32 v[78:79], v[78:79], v[70:71]
	v_pk_mul_f32 v[72:73], v[72:73], v[64:65]
	v_pk_mul_f32 v[74:75], v[74:75], v[66:67]
	v_cvt_pk_bf16_f32 v76, v76, v77
	v_cvt_pk_bf16_f32 v77, v78, v79
	v_cvt_pk_bf16_f32 v78, v72, v73
	v_cvt_pk_bf16_f32 v79, v74, v75
	v_add_u32_e32 v155, 0x42000, v154
	global_store_dwordx4 v155, v[76:79], s[10:11]
	v_pk_mul_f32 v[144:145], v[60:61], v[138:139]
	v_pk_mul_f32 v[146:147], v[62:63], v[138:139]
	v_pk_mul_f32 v[148:149], v[56:57], v[138:139]
	v_pk_mul_f32 v[150:151], v[58:59], v[138:139]
	v_exp_f32_e32 v144, v144
	v_exp_f32_e32 v145, v145
	v_exp_f32_e32 v146, v146
	v_exp_f32_e32 v147, v147
	v_exp_f32_e32 v148, v148
	v_exp_f32_e32 v149, v149
	v_exp_f32_e32 v150, v150
	v_exp_f32_e32 v151, v151
	v_pk_add_f32 v[144:145], v[144:145], v[152:153]
	v_pk_add_f32 v[146:147], v[146:147], v[152:153]
	v_pk_add_f32 v[148:149], v[148:149], v[152:153]
	v_pk_add_f32 v[150:151], v[150:151], v[152:153]
	v_rcp_f32_e32 v144, v144
	v_rcp_f32_e32 v145, v145
	v_rcp_f32_e32 v146, v146
	v_rcp_f32_e32 v147, v147
	v_rcp_f32_e32 v148, v148
	v_rcp_f32_e32 v149, v149
	v_rcp_f32_e32 v150, v150
	v_rcp_f32_e32 v151, v151
	v_pk_mul_f32 v[60:61], v[60:61], v[144:145]
	v_pk_mul_f32 v[62:63], v[62:63], v[146:147]
	v_pk_mul_f32 v[56:57], v[56:57], v[148:149]
	v_pk_mul_f32 v[58:59], v[58:59], v[150:151]
	v_pk_mul_f32 v[60:61], v[60:61], v[52:53]
	v_pk_mul_f32 v[62:63], v[62:63], v[54:55]
	v_pk_mul_f32 v[56:57], v[56:57], v[48:49]
	v_pk_mul_f32 v[58:59], v[58:59], v[50:51]
	v_cvt_pk_bf16_f32 v60, v60, v61
	v_cvt_pk_bf16_f32 v61, v62, v63
	v_cvt_pk_bf16_f32 v62, v56, v57
	v_cvt_pk_bf16_f32 v63, v58, v59
	v_add_u32_e32 v155, 0xb0000, v154
	global_store_dwordx4 v155, v[60:63], s[10:11]
	v_pk_mul_f32 v[144:145], v[44:45], v[138:139]
	v_pk_mul_f32 v[146:147], v[46:47], v[138:139]
	v_pk_mul_f32 v[148:149], v[40:41], v[138:139]
	v_pk_mul_f32 v[150:151], v[42:43], v[138:139]
	v_exp_f32_e32 v144, v144
	v_exp_f32_e32 v145, v145
	v_exp_f32_e32 v146, v146
	v_exp_f32_e32 v147, v147
	v_exp_f32_e32 v148, v148
	v_exp_f32_e32 v149, v149
	v_exp_f32_e32 v150, v150
	v_exp_f32_e32 v151, v151
	v_pk_add_f32 v[144:145], v[144:145], v[152:153]
	v_pk_add_f32 v[146:147], v[146:147], v[152:153]
	v_pk_add_f32 v[148:149], v[148:149], v[152:153]
	v_pk_add_f32 v[150:151], v[150:151], v[152:153]
	v_rcp_f32_e32 v144, v144
	v_rcp_f32_e32 v145, v145
	v_rcp_f32_e32 v146, v146
	v_rcp_f32_e32 v147, v147
	v_rcp_f32_e32 v148, v148
	v_rcp_f32_e32 v149, v149
	v_rcp_f32_e32 v150, v150
	v_rcp_f32_e32 v151, v151
	v_pk_mul_f32 v[44:45], v[44:45], v[144:145]
	v_pk_mul_f32 v[46:47], v[46:47], v[146:147]
	v_pk_mul_f32 v[40:41], v[40:41], v[148:149]
	v_pk_mul_f32 v[42:43], v[42:43], v[150:151]
	v_pk_mul_f32 v[44:45], v[44:45], v[36:37]
	v_pk_mul_f32 v[46:47], v[46:47], v[38:39]
	v_pk_mul_f32 v[40:41], v[40:41], v[32:33]
	v_pk_mul_f32 v[42:43], v[42:43], v[34:35]
	v_cvt_pk_bf16_f32 v44, v44, v45
	v_cvt_pk_bf16_f32 v45, v46, v47
	v_cvt_pk_bf16_f32 v46, v40, v41
	v_cvt_pk_bf16_f32 v47, v42, v43
	v_add_u32_e32 v155, 0xc6000, v154
	global_store_dwordx4 v155, v[44:47], s[10:11]
	v_pk_mul_f32 v[144:145], v[28:29], v[138:139]
	v_pk_mul_f32 v[146:147], v[30:31], v[138:139]
	v_pk_mul_f32 v[148:149], v[24:25], v[138:139]
	v_pk_mul_f32 v[150:151], v[26:27], v[138:139]
	v_exp_f32_e32 v144, v144
	v_exp_f32_e32 v145, v145
	v_exp_f32_e32 v146, v146
	v_exp_f32_e32 v147, v147
	v_exp_f32_e32 v148, v148
	v_exp_f32_e32 v149, v149
	v_exp_f32_e32 v150, v150
	v_exp_f32_e32 v151, v151
	v_pk_add_f32 v[144:145], v[144:145], v[152:153]
	v_pk_add_f32 v[146:147], v[146:147], v[152:153]
	v_pk_add_f32 v[148:149], v[148:149], v[152:153]
	v_pk_add_f32 v[150:151], v[150:151], v[152:153]
	v_rcp_f32_e32 v144, v144
	v_rcp_f32_e32 v145, v145
	v_rcp_f32_e32 v146, v146
	v_rcp_f32_e32 v147, v147
	v_rcp_f32_e32 v148, v148
	v_rcp_f32_e32 v149, v149
	v_rcp_f32_e32 v150, v150
	v_rcp_f32_e32 v151, v151
	v_pk_mul_f32 v[28:29], v[28:29], v[144:145]
	v_pk_mul_f32 v[30:31], v[30:31], v[146:147]
	v_pk_mul_f32 v[24:25], v[24:25], v[148:149]
	v_pk_mul_f32 v[26:27], v[26:27], v[150:151]
	v_pk_mul_f32 v[28:29], v[28:29], v[20:21]
	v_pk_mul_f32 v[30:31], v[30:31], v[22:23]
	v_pk_mul_f32 v[24:25], v[24:25], v[16:17]
	v_pk_mul_f32 v[26:27], v[26:27], v[18:19]
	v_cvt_pk_bf16_f32 v28, v28, v29
	v_cvt_pk_bf16_f32 v29, v30, v31
	v_cvt_pk_bf16_f32 v30, v24, v25
	v_cvt_pk_bf16_f32 v31, v26, v27
	v_add_u32_e32 v155, 0xdc000, v154
	global_store_dwordx4 v155, v[28:31], s[10:11]
	v_pk_mul_f32 v[144:145], v[12:13], v[138:139]
	v_pk_mul_f32 v[146:147], v[14:15], v[138:139]
	v_pk_mul_f32 v[148:149], v[8:9], v[138:139]
	v_pk_mul_f32 v[150:151], v[10:11], v[138:139]
	v_exp_f32_e32 v144, v144
	v_exp_f32_e32 v145, v145
	v_exp_f32_e32 v146, v146
	v_exp_f32_e32 v147, v147
	v_exp_f32_e32 v148, v148
	v_exp_f32_e32 v149, v149
	v_exp_f32_e32 v150, v150
	v_exp_f32_e32 v151, v151
	v_pk_add_f32 v[144:145], v[144:145], v[152:153]
	v_pk_add_f32 v[146:147], v[146:147], v[152:153]
	v_pk_add_f32 v[148:149], v[148:149], v[152:153]
	v_pk_add_f32 v[150:151], v[150:151], v[152:153]
	v_rcp_f32_e32 v144, v144
	v_rcp_f32_e32 v145, v145
	v_rcp_f32_e32 v146, v146
	v_rcp_f32_e32 v147, v147
	v_rcp_f32_e32 v148, v148
	v_rcp_f32_e32 v149, v149
	v_rcp_f32_e32 v150, v150
	v_rcp_f32_e32 v151, v151
	v_pk_mul_f32 v[12:13], v[12:13], v[144:145]
	v_pk_mul_f32 v[14:15], v[14:15], v[146:147]
	v_pk_mul_f32 v[8:9], v[8:9], v[148:149]
	v_pk_mul_f32 v[10:11], v[10:11], v[150:151]
	v_pk_mul_f32 v[12:13], v[12:13], v[4:5]
	v_pk_mul_f32 v[14:15], v[14:15], v[6:7]
	v_pk_mul_f32 v[8:9], v[8:9], v[0:1]
	v_pk_mul_f32 v[10:11], v[10:11], v[2:3]
	v_cvt_pk_bf16_f32 v12, v12, v13
	v_cvt_pk_bf16_f32 v13, v14, v15
	v_cvt_pk_bf16_f32 v14, v8, v9
	v_cvt_pk_bf16_f32 v15, v10, v11
	v_add_u32_e32 v155, 0xf2000, v154
	global_store_dwordx4 v155, v[12:15], s[10:11]
	s_mov_b64 s[4:5], -1
	s_andn2_b64 vcc, exec, s[38:39]
	s_cbranch_vccnz .LBB0_933
	s_andn2_b64 vcc, exec, s[6:7]
	s_cbranch_vccnz .LBB0_932
	s_barrier
	s_branch .LBB0_932
